# all four LayerNorm phases: row-invariant parameter loads hoisted and batched, next-row prefetch; plus adaLN batched loads
# speedup vs baseline: 1.0275x; 1.0133x over previous
; DI void st4(bf16_t* p, float a, float b, float c, float d) { u32x2 w = {pk2(a, b), pk2(c, d)}; *(u32x2*)p = w; }
; DI void phase_ln(const Params& p, const float* g, const float* bta, const float* sh, const float* sc, bool writex, int bid, int nb) {
;     ...
;   for (int row = bid * 8 + wid; row < NTOK; row += nb * 8) {
;     float* xr = p.out + (size_t)row * DM; const int b = row >> 12;
;     f32x4 v[4]; float s = 0.f;
; #pragma unroll
;     for (int e = 0; e < 4; ++e) { v[e] = *(const f32x4*)(xr + e * 256 + lane * 4); s += (v[e][0] + v[e][1]) + (v[e][2] + v[e][3]); }
; #pragma unroll
;     for (int o = 32; o > 0; o >>= 1) s += __shfl_xor(s, o);
;     const float mu = s * (1.f / 1024.f); float q = 0.f;
; #pragma unroll
;     for (int e = 0; e < 4; ++e) { v[e] -= mu; q += (v[e][0] * v[e][0] + v[e][1] * v[e][1]) + (v[e][2] * v[e][2] + v[e][3] * v[e][3]); }
; #pragma unroll
;     for (int o = 32; o > 0; o >>= 1) q += __shfl_xor(q, o);
;     const float rstd = rsqrtf(q * (1.f / 1024.f) + 1e-5f);
;     if (!writex && lane == 0) { f32x2 ms = {mu, rstd}; *(f32x2*)(p.lnstat + (size_t)row * 2) = ms; }
; #pragma unroll
;     for (int e = 0; e < 4; ++e) { const int col = e * 256 + lane * 4;
;       const f32x4 y = v[e] * rstd * *(const f32x4*)(g + col) + *(const f32x4*)(bta + col);
;       if (writex) *(f32x4*)(xr + col) = y;
;       if (sh) { const f32x4 hv = y * (*(const f32x4*)(sc + b * 6144 + col) + 1.f) + *(const f32x4*)(sh + b * 6144 + col); st4(p.H + (size_t)row * DM + col, hv[0], hv[1], hv[2], hv[3]); } }
.LBB0_1070:
	v_mov_b32_e32 v1, v206
	v_readlane_b32 s0, v255, 3
	v_ashrrev_i32_e32 v0, 6, v1
	v_readlane_b32 s1, v255, 4
	v_add_u32_e32 v31, s0, v0
	s_mov_b32 s0, 0x8000
	v_cmp_gt_i32_e32 vcc, s0, v31
	s_and_saveexec_b64 s[2:3], vcc
	s_cbranch_execz .LBB0_1075
	v_cmp_lt_i32_e64 s[0:1], v209, v208
	v_and_b32_e32 v6, 63, v1
	v_readlane_b32 s8, v252, 17
	v_cndmask_b32_e64 v1, v207, v209, s[0:1]
	v_lshlrev_b32_e32 v32, 2, v1
	v_xor_b32_e32 v1, 16, v207
	v_cmp_lt_i32_e64 s[0:1], v1, v208
	v_lshlrev_b32_e32 v2, 4, v6
	v_mov_b32_e32 v3, 0
	v_cndmask_b32_e64 v1, v207, v1, s[0:1]
	v_lshlrev_b32_e32 v33, 2, v1
	v_xor_b32_e32 v1, 8, v207
	v_cmp_lt_i32_e64 s[0:1], v1, v208
	v_readlane_b32 s16, v252, 25
	v_readlane_b32 s17, v252, 26
	v_cndmask_b32_e64 v1, v207, v1, s[0:1]
	v_lshlrev_b32_e32 v34, 2, v1
	v_xor_b32_e32 v1, 4, v207
	v_cmp_lt_i32_e64 s[0:1], v1, v208
	v_lshl_add_u64 v[4:5], s[16:17], 0, v[2:3]
	v_readlane_b32 s9, v252, 18
	v_cndmask_b32_e64 v1, v207, v1, s[0:1]
	v_lshlrev_b32_e32 v35, 2, v1
	v_xor_b32_e32 v1, 2, v207
	v_cmp_lt_i32_e64 s[0:1], v1, v208
	v_readlane_b32 s10, v252, 19
	v_readlane_b32 s11, v252, 20
	v_cndmask_b32_e64 v1, v207, v1, s[0:1]
	v_lshlrev_b32_e32 v36, 2, v1
	v_xor_b32_e32 v1, 1, v207
	v_cmp_lt_i32_e64 s[0:1], v1, v208
	v_readlane_b32 s12, v252, 21
	v_readlane_b32 s13, v252, 22
	v_cndmask_b32_e64 v1, v207, v1, s[0:1]
	s_mov_b64 s[0:1], 0x31000
	v_lshl_add_u64 v[20:21], v[4:5], 0, s[0:1]
	s_mov_b64 s[0:1], 0x30000
	v_lshl_add_u64 v[22:23], v[4:5], 0, s[0:1]
	v_readlane_b32 s0, v255, 3
	v_lshlrev_b32_e32 v37, 2, v1
	v_readlane_b32 s14, v252, 23
	v_readlane_b32 s15, v252, 24
	v_readlane_b32 s18, v252, 27
	v_readlane_b32 s19, v252, 28
	v_readlane_b32 s20, v252, 29
	v_readlane_b32 s21, v252, 30
	v_readlane_b32 s22, v252, 31
	v_readlane_b32 s23, v252, 32
	v_ashrrev_i32_e32 v1, 31, v0
	s_mov_b32 s6, s0
	s_ashr_i32 s7, s0, 31
	v_lshl_add_u64 v[0:1], v[0:1], 0, s[6:7]
	v_readlane_b32 s8, v252, 0
	v_readlane_b32 s1, v255, 4
	v_readlane_b32 s9, v252, 1
	v_lshlrev_b64 v[4:5], 12, v[0:1]
	v_writelane_b32 v255, s0, 3
	v_lshl_add_u64 v[24:25], v[0:1], 3, s[8:9]
	v_or_b32_e32 v4, v4, v2
	v_lshlrev_b64 v[0:1], 11, v[0:1]
	s_lshl_b32 s4, s38, 3
	v_lshl_add_u64 v[16:17], s[80:81], 0, v[2:3]
	v_lshl_add_u64 v[18:19], s[82:83], 0, v[2:3]
	v_writelane_b32 v255, s1, 4
	v_readlane_b32 s14, v252, 6
	v_readlane_b32 s15, v252, 7
	v_lshl_add_u64 v[2:3], s[84:85], 0, v[4:5]
	s_mov_b64 s[0:1], 0x800
	v_lshl_or_b32 v0, v6, 3, v0
	v_readlane_b32 s10, v252, 2
	v_readlane_b32 s11, v252, 3
	v_readlane_b32 s12, v252, 4
	v_readlane_b32 s13, v252, 5
	s_ashr_i32 s5, s4, 31
	v_lshl_add_u64 v[26:27], v[2:3], 0, s[0:1]
	v_lshl_add_u64 v[0:1], s[14:15], 0, v[0:1]
	s_mov_b64 s[0:1], 0x400
	v_cmp_eq_u32_e32 vcc, 0, v6
	s_lshl_b64 s[6:7], s[4:5], 3
	s_lshl_b64 s[8:9], s[4:5], 12
	v_lshl_add_u64 v[28:29], v[0:1], 0, s[0:1]
	s_lshl_b64 s[10:11], s[4:5], 11
	s_mov_b64 s[12:13], 0
	v_mov_b32_e32 v38, 0x3727c5ac
	v_readlane_b32 s16, v252, 8
	v_readlane_b32 s17, v252, 9
	v_readlane_b32 s18, v252, 10
	v_readlane_b32 s19, v252, 11
	v_readlane_b32 s20, v252, 12
	v_readlane_b32 s21, v252, 13
	v_readlane_b32 s22, v252, 14
	v_readlane_b32 s23, v252, 15
	global_load_dwordx4 v[124:127], v[26:27], off offset:-2048
	global_load_dwordx4 v[128:131], v[26:27], off offset:-1024
	global_load_dwordx4 v[132:135], v[26:27], off
	global_load_dwordx4 v[136:139], v[26:27], off offset:1024
	s_waitcnt vmcnt(0)
	s_branch .LBB0_1073
.LBB0_1072:
	s_or_b64 exec, exec, s[0:1]
	s_movk_i32 s0, 0x7fff
	v_lshl_add_u64 v[24:25], v[24:25], 0, s[6:7]
	v_lshl_add_u64 v[26:27], v[26:27], 0, s[8:9]
	s_waitcnt vmcnt(5)
	v_pk_mul_f32 v[46:47], v[14:15], v[30:31] op_sel_hi:[1,0]
	v_pk_mul_f32 v[48:49], v[12:13], v[30:31] op_sel_hi:[1,0]
	v_pk_fma_f32 v[42:43], v[46:47], v[54:55], v[70:71]
	v_pk_fma_f32 v[40:41], v[48:49], v[52:53], v[68:69]
	v_pk_add_f32 v[48:49], v[86:87], 1.0 op_sel_hi:[1,0]
	v_pk_add_f32 v[50:51], v[84:85], 1.0 op_sel_hi:[1,0]
	v_pk_fma_f32 v[14:15], v[42:43], v[48:49], v[102:103]
	v_pk_fma_f32 v[12:13], v[40:41], v[50:51], v[100:101]
	s_nop 0
	v_cvt_pk_bf16_f32 v12, v12, v13
	v_cvt_pk_bf16_f32 v13, v14, v15
	global_store_dwordx2 v[28:29], v[12:13], off offset:-1024
	v_pk_mul_f32 v[46:47], v[10:11], v[30:31] op_sel_hi:[1,0]
	v_pk_mul_f32 v[48:49], v[8:9], v[30:31] op_sel_hi:[1,0]
	v_pk_fma_f32 v[42:43], v[46:47], v[58:59], v[74:75]
	v_pk_fma_f32 v[40:41], v[48:49], v[56:57], v[72:73]
	v_pk_add_f32 v[48:49], v[90:91], 1.0 op_sel_hi:[1,0]
	v_pk_add_f32 v[50:51], v[88:89], 1.0 op_sel_hi:[1,0]
	v_pk_fma_f32 v[10:11], v[42:43], v[48:49], v[106:107]
	v_pk_fma_f32 v[8:9], v[40:41], v[50:51], v[104:105]
	s_nop 0
	v_cvt_pk_bf16_f32 v8, v8, v9
	v_cvt_pk_bf16_f32 v9, v10, v11
	global_store_dwordx2 v[28:29], v[8:9], off offset:-512
	v_pk_mul_f32 v[46:47], v[6:7], v[30:31] op_sel_hi:[1,0]
	v_pk_mul_f32 v[48:49], v[4:5], v[30:31] op_sel_hi:[1,0]
	v_pk_fma_f32 v[42:43], v[46:47], v[62:63], v[78:79]
	v_pk_fma_f32 v[40:41], v[48:49], v[60:61], v[76:77]
	v_pk_add_f32 v[48:49], v[94:95], 1.0 op_sel_hi:[1,0]
	v_pk_add_f32 v[50:51], v[92:93], 1.0 op_sel_hi:[1,0]
	v_pk_fma_f32 v[6:7], v[42:43], v[48:49], v[110:111]
	v_pk_fma_f32 v[4:5], v[40:41], v[50:51], v[108:109]
	s_nop 0
	v_cvt_pk_bf16_f32 v4, v4, v5
	v_cvt_pk_bf16_f32 v5, v6, v7
	global_store_dwordx2 v[28:29], v[4:5], off
	v_pk_mul_f32 v[46:47], v[2:3], v[30:31] op_sel_hi:[1,0]
	v_pk_mul_f32 v[48:49], v[0:1], v[30:31] op_sel_hi:[1,0]
	v_pk_fma_f32 v[42:43], v[46:47], v[66:67], v[82:83]
	v_pk_fma_f32 v[40:41], v[48:49], v[64:65], v[80:81]
	v_pk_add_f32 v[48:49], v[98:99], 1.0 op_sel_hi:[1,0]
	v_pk_add_f32 v[50:51], v[96:97], 1.0 op_sel_hi:[1,0]
	v_pk_fma_f32 v[2:3], v[42:43], v[48:49], v[114:115]
	v_pk_fma_f32 v[0:1], v[40:41], v[50:51], v[112:113]
	s_nop 0
	v_cvt_pk_bf16_f32 v0, v0, v1
	v_cvt_pk_bf16_f32 v1, v2, v3
	global_store_dwordx2 v[28:29], v[0:1], off offset:512
	v_add_u32_e32 v31, s4, v31
	v_cmp_lt_i32_e64 s[0:1], s0, v31
	s_or_b64 s[12:13], s[0:1], s[12:13]
	v_lshl_add_u64 v[28:29], v[28:29], 0, s[10:11]
	s_andn2_b64 exec, exec, s[12:13]
	s_cbranch_execz .LBB0_1075
; DI void phase_ln(const Params& p, const float* g, const float* bta, const float* sh, const float* sc, bool writex, int bid, int nb) {
;     ...
;     float* xr = p.out + (size_t)row * DM; const int b = row >> 12;
;     f32x4 v[4]; float s = 0.f;
; #pragma unroll
;     for (int e = 0; e < 4; ++e) { v[e] = *(const f32x4*)(xr + e * 256 + lane * 4); s += (v[e][0] + v[e][1]) + (v[e][2] + v[e][3]); }
; #pragma unroll
;     for (int o = 32; o > 0; o >>= 1) s += __shfl_xor(s, o);
;     const float mu = s * (1.f / 1024.f); float q = 0.f;
; #pragma unroll
;     for (int e = 0; e < 4; ++e) { v[e] -= mu; q += (v[e][0] * v[e][0] + v[e][1] * v[e][1]) + (v[e][2] * v[e][2] + v[e][3] * v[e][3]); }
; #pragma unroll
;     for (int o = 32; o > 0; o >>= 1) q += __shfl_xor(q, o);
;     const float rstd = rsqrtf(q * (1.f / 1024.f) + 1e-5f);
;     if (!writex && lane == 0) { f32x2 ms = {mu, rstd}; *(f32x2*)(p.lnstat + (size_t)row * 2) = ms; }
.LBB0_1073:
	s_waitcnt vmcnt(5)
	v_mov_b64_e32 v[12:13], v[124:125]
	v_mov_b64_e32 v[14:15], v[126:127]
	v_mov_b64_e32 v[8:9], v[128:129]
	v_mov_b64_e32 v[10:11], v[130:131]
	v_mov_b64_e32 v[4:5], v[132:133]
	v_mov_b64_e32 v[6:7], v[134:135]
	v_mov_b64_e32 v[0:1], v[136:137]
	v_mov_b64_e32 v[2:3], v[138:139]
	v_ashrrev_i32_e32 v116, 12, v31
	v_mul_i32_i24_e32 v116, 0x1800, v116
	v_ashrrev_i32_e32 v117, 31, v116
	v_lshlrev_b64 v[116:117], 2, v[116:117]
	v_lshl_add_u64 v[118:119], v[20:21], 0, v[116:117]
	v_lshl_add_u64 v[116:117], v[22:23], 0, v[116:117]
	global_load_dwordx4 v[52:55], v[16:17], off
	global_load_dwordx4 v[68:71], v[18:19], off
	global_load_dwordx4 v[84:87], v[118:119], off
	global_load_dwordx4 v[100:103], v[116:117], off
	global_load_dwordx4 v[56:59], v[16:17], off offset:1024
	global_load_dwordx4 v[72:75], v[18:19], off offset:1024
	global_load_dwordx4 v[88:91], v[118:119], off offset:1024
	global_load_dwordx4 v[104:107], v[116:117], off offset:1024
	global_load_dwordx4 v[60:63], v[16:17], off offset:2048
	global_load_dwordx4 v[76:79], v[18:19], off offset:2048
	global_load_dwordx4 v[92:95], v[118:119], off offset:2048
	global_load_dwordx4 v[108:111], v[116:117], off offset:2048
	global_load_dwordx4 v[64:67], v[16:17], off offset:3072
	global_load_dwordx4 v[80:83], v[18:19], off offset:3072
	global_load_dwordx4 v[96:99], v[118:119], off offset:3072
	global_load_dwordx4 v[112:115], v[116:117], off offset:3072
	v_add_u32_e32 v140, s4, v31
	s_movk_i32 s100, 0x7fff
	v_cmp_ge_i32_e64 s[98:99], s100, v140
	v_lshl_add_u64 v[142:143], v[26:27], 0, s[8:9]
	s_nop 1
	v_cndmask_b32_e64 v142, v26, v142, s[98:99]
	v_cndmask_b32_e64 v143, v27, v143, s[98:99]
	global_load_dwordx4 v[124:127], v[142:143], off offset:-2048
	global_load_dwordx4 v[128:131], v[142:143], off offset:-1024
	global_load_dwordx4 v[132:135], v[142:143], off
	global_load_dwordx4 v[136:139], v[142:143], off offset:1024
	s_mov_b32 s0, 0x800000
	v_mov_b32_e32 v120, v13
	v_mov_b32_e32 v121, v14
	v_mov_b32_e32 v122, v12
	v_mov_b32_e32 v123, v15
	v_pk_add_f32 v[120:121], v[120:121], v[122:123]
	v_mov_b32_e32 v122, v8
	v_add_f32_e32 v120, v120, v121
	v_add_f32_e32 v40, 0, v120
	v_mov_b32_e32 v120, v9
	v_mov_b32_e32 v121, v10
	v_mov_b32_e32 v123, v11
	v_pk_add_f32 v[120:121], v[120:121], v[122:123]
	s_nop 0
	v_pk_add_f32 v[42:43], v[120:121], v[120:121] op_sel:[0,1] op_sel_hi:[1,0]
	v_add_f32_e32 v44, v4, v5
	v_add_f32_e32 v46, v6, v7
	v_mov_b32_e32 v41, v0
	v_mov_b32_e32 v43, v1
	v_mov_b32_e32 v45, v2
	v_mov_b32_e32 v47, v3
	v_pk_add_f32 v[40:41], v[40:41], v[42:43]
	v_pk_add_f32 v[42:43], v[44:45], v[46:47]
	s_nop 0
	v_pk_add_f32 v[40:41], v[40:41], v[42:43]
	s_nop 0
	v_add_f32_e32 v30, v40, v41
	ds_bpermute_b32 v39, v32, v30
	s_waitcnt lgkmcnt(0)
	v_add_f32_e32 v30, v30, v39
	ds_bpermute_b32 v39, v33, v30
	s_waitcnt lgkmcnt(0)
	v_add_f32_e32 v30, v30, v39
	ds_bpermute_b32 v39, v34, v30
	s_waitcnt lgkmcnt(0)
	v_add_f32_e32 v30, v30, v39
	ds_bpermute_b32 v39, v35, v30
	s_waitcnt lgkmcnt(0)
	v_add_f32_e32 v30, v30, v39
	ds_bpermute_b32 v39, v36, v30
	s_waitcnt lgkmcnt(0)
	v_add_f32_e32 v30, v30, v39
	ds_bpermute_b32 v39, v37, v30
	s_waitcnt lgkmcnt(0)
	v_add_f32_e32 v39, v30, v39
	v_fmamk_f32 v15, v39, 0xba800000, v15
	v_fmamk_f32 v14, v39, 0xba800000, v14
	v_fmamk_f32 v13, v39, 0xba800000, v13
	v_fmac_f32_e32 v12, 0xba800000, v39
	v_pk_mul_f32 v[40:41], v[14:15], v[14:15]
	v_pk_mul_f32 v[42:43], v[12:13], v[12:13]
	v_fmamk_f32 v11, v39, 0xba800000, v11
	v_pk_mov_b32 v[44:45], v[42:43], v[40:41] op_sel:[1,0]
	v_mov_b32_e32 v43, v41
	v_fmamk_f32 v10, v39, 0xba800000, v10
	v_fmamk_f32 v9, v39, 0xba800000, v9
	v_fmac_f32_e32 v8, 0xba800000, v39
	v_pk_add_f32 v[40:41], v[44:45], v[42:43]
	v_pk_mul_f32 v[42:43], v[10:11], v[10:11]
	v_pk_mul_f32 v[44:45], v[8:9], v[8:9]
	v_fmac_f32_e32 v4, 0xba800000, v39
	v_pk_mov_b32 v[46:47], v[44:45], v[42:43] op_sel:[1,0]
	v_mov_b32_e32 v45, v43
	v_fmamk_f32 v6, v39, 0xba800000, v6
	v_fmamk_f32 v5, v39, 0xba800000, v5
	v_mul_f32_e32 v30, v4, v4
	v_pk_add_f32 v[42:43], v[46:47], v[44:45]
	v_fmamk_f32 v7, v39, 0xba800000, v7
	v_pk_fma_f32 v[44:45], v[4:5], v[4:5], v[30:31] op_sel_hi:[1,1,0]
	v_mul_f32_e32 v30, v6, v6
	v_pk_add_f32 v[40:41], v[40:41], v[40:41] op_sel_hi:[0,1]
	v_pk_add_f32 v[42:43], v[42:43], v[42:43] op_sel_hi:[0,1]
	v_pk_fma_f32 v[46:47], v[6:7], v[6:7], v[30:31] op_sel_hi:[1,1,0]
	v_fmamk_f32 v3, v39, 0xba800000, v3
	v_fmamk_f32 v2, v39, 0xba800000, v2
	v_fmamk_f32 v1, v39, 0xba800000, v1
	v_fmac_f32_e32 v0, 0xba800000, v39
	v_mul_f32_e32 v44, v0, v0
	v_mul_f32_e32 v46, v1, v1
	v_mul_f32_e32 v40, v2, v2
	v_mul_f32_e32 v42, v3, v3
	v_pk_add_f32 v[44:45], v[44:45], v[46:47]
	v_pk_add_f32 v[40:41], v[40:41], v[42:43]
	s_nop 0
	v_pk_add_f32 v[40:41], v[44:45], v[40:41]
	s_nop 0
	v_add_f32_e32 v30, v40, v41
	ds_bpermute_b32 v40, v32, v30
	s_waitcnt lgkmcnt(0)
	v_add_f32_e32 v30, v30, v40
	ds_bpermute_b32 v40, v33, v30
	s_waitcnt lgkmcnt(0)
	v_add_f32_e32 v30, v30, v40
	ds_bpermute_b32 v40, v34, v30
	s_waitcnt lgkmcnt(0)
	v_add_f32_e32 v30, v30, v40
	ds_bpermute_b32 v40, v35, v30
	s_waitcnt lgkmcnt(0)
	v_add_f32_e32 v30, v30, v40
	ds_bpermute_b32 v40, v36, v30
	s_waitcnt lgkmcnt(0)
	v_add_f32_e32 v30, v30, v40
	ds_bpermute_b32 v40, v37, v30
	s_waitcnt lgkmcnt(0)
	v_add_f32_e32 v30, v30, v40
	v_fmamk_f32 v30, v30, 0x3a800000, v38
	v_cmp_gt_f32_e64 s[0:1], s0, v30
	v_mul_f32_e32 v40, 0x4b800000, v30
	s_nop 0
	v_cndmask_b32_e64 v30, v30, v40, s[0:1]
	v_rsq_f32_e32 v30, v30
	s_nop 0
	v_mul_f32_e32 v40, 0x45800000, v30
	v_cndmask_b32_e64 v30, v30, v40, s[0:1]
	s_and_saveexec_b64 s[0:1], vcc
	s_cbranch_execz .LBB0_1072
	v_mul_f32_e32 v40, 0x3a800000, v39
	v_mov_b32_e32 v41, v30
	global_store_dwordx2 v[24:25], v[40:41], off
	s_branch .LBB0_1072

; DI int tidx() { int t = __builtin_amdgcn_workitem_id_x(); asm volatile("" : "+v"(t)); return t; }
; DI void st4(bf16_t* p, float a, float b, float c, float d) { u32x2 w = {pk2(a, b), pk2(c, d)}; *(u32x2*)p = w; }
; DI void phase_ln(const Params& p, const float* g, const float* bta, const float* sh, const float* sc, bool writex, int bid, int nb) {
;   const int tid = tidx(), lane = tid & 63, wid = tid >> 6;
;   for (int row = bid * 8 + wid; row < NTOK; row += nb * 8) {
;     float* xr = p.out + (size_t)row * DM; const int b = row >> 12;
;     f32x4 v[4]; float s = 0.f;
; #pragma unroll
;     for (int e = 0; e < 4; ++e) { v[e] = *(const f32x4*)(xr + e * 256 + lane * 4); s += (v[e][0] + v[e][1]) + (v[e][2] + v[e][3]); }
; #pragma unroll
;     for (int o = 32; o > 0; o >>= 1) s += __shfl_xor(s, o);
;     const float mu = s * (1.f / 1024.f); float q = 0.f;
; #pragma unroll
;     for (int e = 0; e < 4; ++e) { v[e] -= mu; q += (v[e][0] * v[e][0] + v[e][1] * v[e][1]) + (v[e][2] * v[e][2] + v[e][3] * v[e][3]); }
; #pragma unroll
;     for (int o = 32; o > 0; o >>= 1) q += __shfl_xor(q, o);
;     const float rstd = rsqrtf(q * (1.f / 1024.f) + 1e-5f);
;     if (!writex && lane == 0) { f32x2 ms = {mu, rstd}; *(f32x2*)(p.lnstat + (size_t)row * 2) = ms; }
; #pragma unroll
;     for (int e = 0; e < 4; ++e) { const int col = e * 256 + lane * 4;
;       const f32x4 y = v[e] * rstd * *(const f32x4*)(g + col) + *(const f32x4*)(bta + col);
;       if (writex) *(f32x4*)(xr + col) = y;
;       if (sh) { const f32x4 hv = y * (*(const f32x4*)(sc + b * 6144 + col) + 1.f) + *(const f32x4*)(sh + b * 6144 + col); st4(p.H + (size_t)row * DM + col, hv[0], hv[1], hv[2], hv[3]); } }
.LBB0_1828:
	s_or_b64 exec, exec, s[0:1]
	v_mov_b32_e32 v1, v206
	s_waitcnt lgkmcnt(0)
	s_barrier
	s_mov_b32 s0, 0x8000
	v_ashrrev_i32_e32 v0, 6, v1
	v_add_u32_e32 v43, s94, v0
	v_cmp_gt_i32_e32 vcc, s0, v43
	s_and_saveexec_b64 s[2:3], vcc
	s_cbranch_execz .LBB0_1833
	v_readlane_b32 s4, v252, 60
	v_readlane_b32 s12, v251, 4
	v_readlane_b32 s13, v251, 5
	v_readlane_b32 s14, v251, 6
	v_readlane_b32 s15, v251, 7
	v_readlane_b32 s16, v251, 8
	v_readlane_b32 s17, v251, 9
	v_readlane_b32 s18, v251, 10
	v_readlane_b32 s19, v251, 11
	s_mov_b64 s[12:13], s[16:17]
	v_readlane_b32 s6, v252, 62
	s_mov_b64 s[14:15], s[18:19]
	v_readlane_b32 s7, v252, 63
	s_add_u32 s6, s14, 0x1000
	v_readlane_b32 s8, v251, 0
	s_addc_u32 s7, s15, 0
	v_readlane_b32 s0, v251, 16
	v_readlane_b32 s9, v251, 1
	s_add_u32 s8, s12, 0x1000
	v_readlane_b32 s1, v251, 17
	s_addc_u32 s9, s13, 0
	s_lshl_b32 s4, s0, 3
	v_cmp_lt_i32_e64 s[0:1], v209, v208
	v_and_b32_e32 v6, 63, v1
	v_lshlrev_b32_e32 v2, 4, v6
	v_cndmask_b32_e64 v1, v207, v209, s[0:1]
	v_lshlrev_b32_e32 v44, 2, v1
	v_xor_b32_e32 v1, 16, v207
	v_cmp_lt_i32_e64 s[0:1], v1, v208
	v_mov_b32_e32 v3, 0
	v_or_b32_e32 v4, 0x400, v2
	v_cndmask_b32_e64 v1, v207, v1, s[0:1]
	v_lshlrev_b32_e32 v45, 2, v1
	v_xor_b32_e32 v1, 8, v207
	v_cmp_lt_i32_e64 s[0:1], v1, v208
	v_mov_b32_e32 v5, v3
	v_lshl_add_u64 v[20:21], s[8:9], 0, v[4:5]
	v_cndmask_b32_e64 v1, v207, v1, s[0:1]
	v_lshlrev_b32_e32 v46, 2, v1
	v_xor_b32_e32 v1, 4, v207
	v_cmp_lt_i32_e64 s[0:1], v1, v208
	v_lshl_add_u64 v[22:23], s[6:7], 0, v[4:5]
	v_or_b32_e32 v4, 0x800, v2
	v_cndmask_b32_e64 v1, v207, v1, s[0:1]
	v_lshlrev_b32_e32 v47, 2, v1
	v_xor_b32_e32 v1, 2, v207
	v_cmp_lt_i32_e64 s[0:1], v1, v208
	v_readlane_b32 s10, v251, 2
	v_readlane_b32 s11, v251, 3
	v_cndmask_b32_e64 v1, v207, v1, s[0:1]
	v_lshlrev_b32_e32 v48, 2, v1
	v_xor_b32_e32 v1, 1, v207
	v_lshl_add_u64 v[24:25], s[8:9], 0, v[4:5]
	v_lshl_add_u64 v[26:27], s[6:7], 0, v[4:5]
	v_or_b32_e32 v4, 0xc00, v2
	v_cmp_lt_i32_e64 s[0:1], v1, v208
	v_lshl_add_u64 v[16:17], s[8:9], 0, v[2:3]
	v_lshl_add_u64 v[28:29], s[8:9], 0, v[4:5]
	v_readlane_b32 s8, v252, 17
	v_cndmask_b32_e64 v1, v207, v1, s[0:1]
	v_readlane_b32 s9, v252, 18
	v_readlane_b32 s10, v252, 19
	v_readlane_b32 s11, v252, 20
	v_readlane_b32 s12, v252, 21
	v_readlane_b32 s13, v252, 22
	v_readlane_b32 s14, v252, 23
	v_readlane_b32 s15, v252, 24
	v_readlane_b32 s16, v252, 25
	v_readlane_b32 s17, v252, 26
	v_readlane_b32 s18, v252, 27
	v_readlane_b32 s19, v252, 28
	v_readlane_b32 s20, v252, 29
	v_readlane_b32 s21, v252, 30
	v_readlane_b32 s22, v252, 31
	v_readlane_b32 s23, v252, 32
	v_lshlrev_b32_e32 v49, 2, v1
	v_lshl_add_u64 v[30:31], s[6:7], 0, v[4:5]
	v_lshl_add_u64 v[4:5], s[16:17], 0, v[2:3]
	s_mov_b64 s[0:1], 0x34000
	v_ashrrev_i32_e32 v1, 31, v0
	s_ashr_i32 s95, s94, 31
	v_readlane_b32 s8, v252, 0
	v_lshl_add_u64 v[32:33], v[4:5], 0, s[0:1]
	s_mov_b64 s[0:1], 0x33000
	v_lshl_add_u64 v[0:1], v[0:1], 0, s[94:95]
	v_readlane_b32 s16, v252, 8
	v_readlane_b32 s17, v252, 9
	v_readlane_b32 s18, v252, 10
	v_readlane_b32 s19, v252, 11
	v_readlane_b32 s20, v252, 12
	v_readlane_b32 s21, v252, 13
	v_readlane_b32 s22, v252, 14
	v_readlane_b32 s23, v252, 15
	v_lshl_add_u64 v[34:35], v[4:5], 0, s[0:1]
	v_readlane_b32 s9, v252, 1
	v_lshlrev_b64 v[4:5], 12, v[0:1]
	v_readlane_b32 s16, v251, 19
	v_lshl_add_u64 v[36:37], v[0:1], 3, s[8:9]
	v_or_b32_e32 v4, v4, v2
	v_readlane_b32 s24, v251, 27
	v_readlane_b32 s25, v251, 28
	v_lshlrev_b64 v[0:1], 11, v[0:1]
	v_readlane_b32 s5, v252, 61
	v_lshl_add_u64 v[18:19], s[6:7], 0, v[2:3]
	v_readlane_b32 s14, v252, 6
	v_readlane_b32 s15, v252, 7
	v_lshl_add_u64 v[2:3], s[24:25], 0, v[4:5]
	s_mov_b64 s[0:1], 0x800
	v_lshl_or_b32 v0, v6, 3, v0
	v_readlane_b32 s10, v252, 2
	v_readlane_b32 s11, v252, 3
	v_readlane_b32 s12, v252, 4
	v_readlane_b32 s13, v252, 5
	s_ashr_i32 s5, s4, 31
	v_lshl_add_u64 v[38:39], v[2:3], 0, s[0:1]
	v_lshl_add_u64 v[0:1], s[14:15], 0, v[0:1]
	s_mov_b64 s[0:1], 0x400
	v_cmp_eq_u32_e32 vcc, 0, v6
	s_lshl_b64 s[6:7], s[4:5], 3
	s_lshl_b64 s[8:9], s[4:5], 12
	v_lshl_add_u64 v[40:41], v[0:1], 0, s[0:1]
	s_lshl_b64 s[10:11], s[4:5], 11
	s_mov_b64 s[12:13], 0
	v_mov_b32_e32 v50, 0x3727c5ac
	s_mov_b32 s5, 0x800000
	s_movk_i32 s14, 0x7fff
	v_readlane_b32 s17, v251, 20
	v_readlane_b32 s18, v251, 21
	v_readlane_b32 s19, v251, 22
	v_readlane_b32 s20, v251, 23
	v_readlane_b32 s21, v251, 24
	v_readlane_b32 s22, v251, 25
	v_readlane_b32 s23, v251, 26
	v_readlane_b32 s26, v251, 29
	v_readlane_b32 s27, v251, 30
	v_readlane_b32 s28, v251, 31
	v_readlane_b32 s29, v251, 32
	v_readlane_b32 s30, v251, 33
	v_readlane_b32 s31, v251, 34
	global_load_dwordx4 v[136:139], v[38:39], off offset:-2048
	global_load_dwordx4 v[140:143], v[38:39], off offset:-1024
	global_load_dwordx4 v[144:147], v[38:39], off
	global_load_dwordx4 v[148:151], v[38:39], off offset:1024
	s_waitcnt vmcnt(0)
	s_branch .LBB0_1831
; DI void st4(bf16_t* p, float a, float b, float c, float d) { u32x2 w = {pk2(a, b), pk2(c, d)}; *(u32x2*)p = w; }
; DI void phase_ln(const Params& p, const float* g, const float* bta, const float* sh, const float* sc, bool writex, int bid, int nb) {
;     ...
; #pragma unroll
;     for (int e = 0; e < 4; ++e) { const int col = e * 256 + lane * 4;
;       const f32x4 y = v[e] * rstd * *(const f32x4*)(g + col) + *(const f32x4*)(bta + col);
;       if (writex) *(f32x4*)(xr + col) = y;
;       if (sh) { const f32x4 hv = y * (*(const f32x4*)(sc + b * 6144 + col) + 1.f) + *(const f32x4*)(sh + b * 6144 + col); st4(p.H + (size_t)row * DM + col, hv[0], hv[1], hv[2], hv[3]); } }
.LBB0_1830:
	s_or_b64 exec, exec, s[0:1]
	v_pk_mul_f32 v[14:15], v[14:15], v[42:43] op_sel_hi:[1,0]
	v_pk_mul_f32 v[12:13], v[12:13], v[42:43] op_sel_hi:[1,0]
	v_pk_mul_f32 v[10:11], v[10:11], v[42:43] op_sel_hi:[1,0]
	v_pk_mul_f32 v[8:9], v[8:9], v[42:43] op_sel_hi:[1,0]
	v_pk_mul_f32 v[6:7], v[6:7], v[42:43] op_sel_hi:[1,0]
	v_pk_mul_f32 v[4:5], v[4:5], v[42:43] op_sel_hi:[1,0]
	v_pk_mul_f32 v[2:3], v[2:3], v[42:43] op_sel_hi:[1,0]
	v_pk_mul_f32 v[0:1], v[0:1], v[42:43] op_sel_hi:[1,0]
	v_add_u32_e32 v43, s4, v43
	v_cmp_lt_i32_e64 s[0:1], s14, v43
	v_lshl_add_u64 v[36:37], v[36:37], 0, s[6:7]
	v_lshl_add_u64 v[38:39], v[38:39], 0, s[8:9]
	s_or_b64 s[12:13], s[0:1], s[12:13]
	s_waitcnt vmcnt(5)
	v_pk_fma_f32 v[14:15], v[14:15], v[74:75], v[90:91]
	v_pk_fma_f32 v[12:13], v[12:13], v[72:73], v[88:89]
	v_pk_add_f32 v[152:153], v[106:107], 1.0 op_sel_hi:[1,0]
	v_pk_add_f32 v[154:155], v[104:105], 1.0 op_sel_hi:[1,0]
	v_pk_fma_f32 v[14:15], v[14:15], v[152:153], v[122:123]
	v_pk_fma_f32 v[12:13], v[12:13], v[154:155], v[120:121]
	s_nop 0
	v_cvt_pk_bf16_f32 v12, v12, v13
	v_cvt_pk_bf16_f32 v13, v14, v15
	global_store_dwordx2 v[40:41], v[12:13], off offset:-1024
	v_pk_fma_f32 v[10:11], v[10:11], v[78:79], v[94:95]
	v_pk_fma_f32 v[8:9], v[8:9], v[76:77], v[92:93]
	v_pk_add_f32 v[152:153], v[110:111], 1.0 op_sel_hi:[1,0]
	v_pk_add_f32 v[154:155], v[108:109], 1.0 op_sel_hi:[1,0]
	v_pk_fma_f32 v[10:11], v[10:11], v[152:153], v[126:127]
	v_pk_fma_f32 v[8:9], v[8:9], v[154:155], v[124:125]
	s_nop 0
	v_cvt_pk_bf16_f32 v8, v8, v9
	v_cvt_pk_bf16_f32 v9, v10, v11
	global_store_dwordx2 v[40:41], v[8:9], off offset:-512
	v_pk_fma_f32 v[6:7], v[6:7], v[82:83], v[98:99]
	v_pk_fma_f32 v[4:5], v[4:5], v[80:81], v[96:97]
	v_pk_add_f32 v[152:153], v[114:115], 1.0 op_sel_hi:[1,0]
	v_pk_add_f32 v[154:155], v[112:113], 1.0 op_sel_hi:[1,0]
	v_pk_fma_f32 v[6:7], v[6:7], v[152:153], v[130:131]
	v_pk_fma_f32 v[4:5], v[4:5], v[154:155], v[128:129]
	s_nop 0
	v_cvt_pk_bf16_f32 v4, v4, v5
	v_cvt_pk_bf16_f32 v5, v6, v7
	global_store_dwordx2 v[40:41], v[4:5], off
	v_pk_fma_f32 v[2:3], v[2:3], v[86:87], v[102:103]
	v_pk_fma_f32 v[0:1], v[0:1], v[84:85], v[100:101]
	v_pk_add_f32 v[152:153], v[118:119], 1.0 op_sel_hi:[1,0]
	v_pk_add_f32 v[154:155], v[116:117], 1.0 op_sel_hi:[1,0]
	v_pk_fma_f32 v[2:3], v[2:3], v[152:153], v[134:135]
	v_pk_fma_f32 v[0:1], v[0:1], v[154:155], v[132:133]
	s_nop 0
	v_cvt_pk_bf16_f32 v0, v0, v1
	v_cvt_pk_bf16_f32 v1, v2, v3
	global_store_dwordx2 v[40:41], v[0:1], off offset:512
	v_lshl_add_u64 v[40:41], v[40:41], 0, s[10:11]
	s_andn2_b64 exec, exec, s[12:13]
	s_cbranch_execz .LBB0_1833
; DI void phase_ln(const Params& p, const float* g, const float* bta, const float* sh, const float* sc, bool writex, int bid, int nb) {
;     ...
;     float* xr = p.out + (size_t)row * DM; const int b = row >> 12;
;     f32x4 v[4]; float s = 0.f;
; #pragma unroll
;     for (int e = 0; e < 4; ++e) { v[e] = *(const f32x4*)(xr + e * 256 + lane * 4); s += (v[e][0] + v[e][1]) + (v[e][2] + v[e][3]); }
; #pragma unroll
;     for (int o = 32; o > 0; o >>= 1) s += __shfl_xor(s, o);
;     const float mu = s * (1.f / 1024.f); float q = 0.f;
; #pragma unroll
;     for (int e = 0; e < 4; ++e) { v[e] -= mu; q += (v[e][0] * v[e][0] + v[e][1] * v[e][1]) + (v[e][2] * v[e][2] + v[e][3] * v[e][3]); }
; #pragma unroll
;     for (int o = 32; o > 0; o >>= 1) q += __shfl_xor(q, o);
;     const float rstd = rsqrtf(q * (1.f / 1024.f) + 1e-5f);
;     if (!writex && lane == 0) { f32x2 ms = {mu, rstd}; *(f32x2*)(p.lnstat + (size_t)row * 2) = ms; }
.LBB0_1831:
	s_waitcnt vmcnt(5)
	v_mov_b64_e32 v[12:13], v[136:137]
	v_mov_b64_e32 v[14:15], v[138:139]
	v_mov_b64_e32 v[8:9], v[140:141]
	v_mov_b64_e32 v[10:11], v[142:143]
	v_mov_b64_e32 v[4:5], v[144:145]
	v_mov_b64_e32 v[6:7], v[146:147]
	v_mov_b64_e32 v[0:1], v[148:149]
	v_mov_b64_e32 v[2:3], v[150:151]
	v_ashrrev_i32_e32 v156, 12, v43
	v_mul_i32_i24_e32 v156, 0x1800, v156
	v_ashrrev_i32_e32 v157, 31, v156
	v_lshlrev_b64 v[156:157], 2, v[156:157]
	v_lshl_add_u64 v[158:159], v[32:33], 0, v[156:157]
	v_lshl_add_u64 v[156:157], v[34:35], 0, v[156:157]
	global_load_dwordx4 v[72:75], v[16:17], off
	global_load_dwordx4 v[88:91], v[18:19], off
	global_load_dwordx4 v[104:107], v[158:159], off
	global_load_dwordx4 v[120:123], v[156:157], off
	global_load_dwordx4 v[76:79], v[20:21], off
	global_load_dwordx4 v[92:95], v[22:23], off
	global_load_dwordx4 v[108:111], v[158:159], off offset:1024
	global_load_dwordx4 v[124:127], v[156:157], off offset:1024
	global_load_dwordx4 v[80:83], v[24:25], off
	global_load_dwordx4 v[96:99], v[26:27], off
	global_load_dwordx4 v[112:115], v[158:159], off offset:2048
	global_load_dwordx4 v[128:131], v[156:157], off offset:2048
	global_load_dwordx4 v[84:87], v[28:29], off
	global_load_dwordx4 v[100:103], v[30:31], off
	global_load_dwordx4 v[116:119], v[158:159], off offset:3072
	global_load_dwordx4 v[132:135], v[156:157], off offset:3072
	v_add_u32_e32 v160, s4, v43
	v_cmp_ge_i32_e64 s[98:99], s14, v160
	v_lshl_add_u64 v[162:163], v[38:39], 0, s[8:9]
	s_nop 1
	v_cndmask_b32_e64 v162, v38, v162, s[98:99]
	v_cndmask_b32_e64 v163, v39, v163, s[98:99]
	global_load_dwordx4 v[136:139], v[162:163], off offset:-2048
	global_load_dwordx4 v[140:143], v[162:163], off offset:-1024
	global_load_dwordx4 v[144:147], v[162:163], off
	global_load_dwordx4 v[148:151], v[162:163], off offset:1024
	v_mov_b32_e32 v52, v13
	v_mov_b32_e32 v53, v14
	v_mov_b32_e32 v54, v12
	v_mov_b32_e32 v55, v15
	v_mov_b32_e32 v56, v9
	v_mov_b32_e32 v57, v10
	v_mov_b32_e32 v58, v8
	v_mov_b32_e32 v59, v11
	v_pk_add_f32 v[52:53], v[52:53], v[54:55]
	v_pk_add_f32 v[54:55], v[56:57], v[58:59]
	v_add_f32_e32 v42, v52, v53
	v_pk_add_f32 v[52:53], v[54:55], v[54:55] op_sel:[0,1] op_sel_hi:[1,0]
	v_add_f32_e32 v60, v4, v5
	v_add_f32_e32 v62, v6, v7
	v_mov_b32_e32 v65, v0
	v_mov_b32_e32 v61, v2
	v_mov_b32_e32 v63, v3
	v_add_f32_e32 v64, 0, v42
	v_mov_b32_e32 v53, v1
	v_pk_add_f32 v[56:57], v[60:61], v[62:63]
	v_pk_add_f32 v[52:53], v[64:65], v[52:53]
	s_nop 0
	v_pk_add_f32 v[52:53], v[52:53], v[56:57]
	s_nop 0
	v_add_f32_e32 v42, v52, v53
	ds_bpermute_b32 v51, v44, v42
	s_waitcnt lgkmcnt(0)
	v_add_f32_e32 v42, v42, v51
	ds_bpermute_b32 v51, v45, v42
	s_waitcnt lgkmcnt(0)
	v_add_f32_e32 v42, v42, v51
	ds_bpermute_b32 v51, v46, v42
	s_waitcnt lgkmcnt(0)
	v_add_f32_e32 v42, v42, v51
	ds_bpermute_b32 v51, v47, v42
	s_waitcnt lgkmcnt(0)
	v_add_f32_e32 v42, v42, v51
	ds_bpermute_b32 v51, v48, v42
	s_waitcnt lgkmcnt(0)
	v_add_f32_e32 v42, v42, v51
	ds_bpermute_b32 v51, v49, v42
	s_waitcnt lgkmcnt(0)
	v_add_f32_e32 v51, v42, v51
	v_fmamk_f32 v15, v51, 0xba800000, v15
	v_fmamk_f32 v14, v51, 0xba800000, v14
	v_fmamk_f32 v13, v51, 0xba800000, v13
	v_fmac_f32_e32 v12, 0xba800000, v51
	v_fmamk_f32 v11, v51, 0xba800000, v11
	v_fmamk_f32 v10, v51, 0xba800000, v10
	v_fmamk_f32 v9, v51, 0xba800000, v9
	v_fmac_f32_e32 v8, 0xba800000, v51
	v_pk_mul_f32 v[52:53], v[14:15], v[14:15]
	v_pk_mul_f32 v[54:55], v[12:13], v[12:13]
	v_pk_mul_f32 v[56:57], v[10:11], v[10:11]
	v_pk_mul_f32 v[58:59], v[8:9], v[8:9]
	v_fmamk_f32 v6, v51, 0xba800000, v6
	v_fmac_f32_e32 v4, 0xba800000, v51
	v_pk_mov_b32 v[62:63], v[54:55], v[52:53] op_sel:[1,0]
	v_mov_b32_e32 v55, v53
	v_pk_mov_b32 v[52:53], v[58:59], v[56:57] op_sel:[1,0]
	v_mov_b32_e32 v59, v57
	v_fmamk_f32 v7, v51, 0xba800000, v7
	v_fmamk_f32 v5, v51, 0xba800000, v5
	v_mul_f32_e32 v42, v4, v4
	v_mul_f32_e32 v60, v6, v6
	v_pk_add_f32 v[54:55], v[62:63], v[54:55]
	v_pk_add_f32 v[52:53], v[52:53], v[58:59]
	v_fmamk_f32 v3, v51, 0xba800000, v3
	v_fmamk_f32 v2, v51, 0xba800000, v2
	v_fmamk_f32 v1, v51, 0xba800000, v1
	v_fmac_f32_e32 v0, 0xba800000, v51
	v_pk_fma_f32 v[56:57], v[4:5], v[4:5], v[42:43] op_sel_hi:[1,1,0]
	v_pk_fma_f32 v[60:61], v[6:7], v[6:7], v[60:61] op_sel_hi:[1,1,0]
	v_pk_add_f32 v[54:55], v[54:55], v[54:55] op_sel_hi:[0,1]
	v_pk_add_f32 v[52:53], v[52:53], v[52:53] op_sel_hi:[0,1]
	v_mul_f32_e32 v56, v0, v0
	v_mul_f32_e32 v60, v1, v1
	v_mul_f32_e32 v54, v2, v2
	v_mul_f32_e32 v52, v3, v3
	v_pk_add_f32 v[56:57], v[56:57], v[60:61]
	v_pk_add_f32 v[52:53], v[54:55], v[52:53]
	s_nop 0
	v_pk_add_f32 v[52:53], v[56:57], v[52:53]
	s_nop 0
	v_add_f32_e32 v42, v52, v53
	ds_bpermute_b32 v52, v44, v42
	s_waitcnt lgkmcnt(0)
	v_add_f32_e32 v42, v42, v52
	ds_bpermute_b32 v52, v45, v42
	s_waitcnt lgkmcnt(0)
	v_add_f32_e32 v42, v42, v52
	ds_bpermute_b32 v52, v46, v42
	s_waitcnt lgkmcnt(0)
	v_add_f32_e32 v42, v42, v52
	ds_bpermute_b32 v52, v47, v42
	s_waitcnt lgkmcnt(0)
	v_add_f32_e32 v42, v42, v52
	ds_bpermute_b32 v52, v48, v42
	s_waitcnt lgkmcnt(0)
	v_add_f32_e32 v42, v42, v52
	ds_bpermute_b32 v52, v49, v42
	s_waitcnt lgkmcnt(0)
	v_add_f32_e32 v42, v42, v52
	v_fmamk_f32 v42, v42, 0x3a800000, v50
	v_mul_f32_e32 v52, 0x4b800000, v42
	v_cmp_gt_f32_e64 s[0:1], s5, v42
	s_nop 1
	v_cndmask_b32_e64 v42, v42, v52, s[0:1]
	v_rsq_f32_e32 v42, v42
	s_nop 0
	v_mul_f32_e32 v52, 0x45800000, v42
	v_cndmask_b32_e64 v42, v42, v52, s[0:1]
	s_and_saveexec_b64 s[0:1], vcc
	s_cbranch_execz .LBB0_1830
	v_mul_f32_e32 v52, 0x3a800000, v51
	v_mov_b32_e32 v53, v42
	global_store_dwordx2 v[36:37], v[52:53], off
	s_branch .LBB0_1830

; DI int tidx() { int t = __builtin_amdgcn_workitem_id_x(); asm volatile("" : "+v"(t)); return t; }
; DI void phase_ln(const Params& p, const float* g, const float* bta, const float* sh, const float* sc, bool writex, int bid, int nb) {
;   const int tid = tidx(), lane = tid & 63, wid = tid >> 6;
;   for (int row = bid * 8 + wid; row < NTOK; row += nb * 8) {
;     float* xr = p.out + (size_t)row * DM; const int b = row >> 12;
;     f32x4 v[4]; float s = 0.f;
; #pragma unroll
;     for (int e = 0; e < 4; ++e) { v[e] = *(const f32x4*)(xr + e * 256 + lane * 4); s += (v[e][0] + v[e][1]) + (v[e][2] + v[e][3]); }
; #pragma unroll
;     for (int o = 32; o > 0; o >>= 1) s += __shfl_xor(s, o);
;     const float mu = s * (1.f / 1024.f); float q = 0.f;
; #pragma unroll
;     for (int e = 0; e < 4; ++e) { v[e] -= mu; q += (v[e][0] * v[e][0] + v[e][1] * v[e][1]) + (v[e][2] * v[e][2] + v[e][3] * v[e][3]); }
; #pragma unroll
;     for (int o = 32; o > 0; o >>= 1) q += __shfl_xor(q, o);
;     const float rstd = rsqrtf(q * (1.f / 1024.f) + 1e-5f);
;     if (!writex && lane == 0) { f32x2 ms = {mu, rstd}; *(f32x2*)(p.lnstat + (size_t)row * 2) = ms; }
; #pragma unroll
;     for (int e = 0; e < 4; ++e) { const int col = e * 256 + lane * 4;
;       const f32x4 y = v[e] * rstd * *(const f32x4*)(g + col) + *(const f32x4*)(bta + col);
;       if (writex) *(f32x4*)(xr + col) = y;
.LBB0_2109:
	s_or_b64 exec, exec, s[0:1]
	s_waitcnt lgkmcnt(0)
	s_barrier
	s_mov_b32 s0, 0x8000
	v_ashrrev_i32_e32 v0, 6, v206
	v_add_u32_e32 v22, s94, v0
	v_cmp_gt_i32_e32 vcc, s0, v22
	s_and_saveexec_b64 s[0:1], vcc
	s_cbranch_execz .LBB0_2112
	v_cmp_lt_i32_e32 vcc, v209, v208
	v_readlane_b32 s0, v251, 19
	v_readlane_b32 s2, v251, 21
	v_cndmask_b32_e32 v1, v207, v209, vcc
	v_lshlrev_b32_e32 v23, 2, v1
	v_xor_b32_e32 v1, 16, v207
	v_cmp_lt_i32_e32 vcc, v1, v208
	v_readlane_b32 s6, v251, 25
	v_readlane_b32 s3, v251, 22
	v_cndmask_b32_e32 v1, v207, v1, vcc
	v_lshlrev_b32_e32 v24, 2, v1
	v_xor_b32_e32 v1, 8, v207
	v_cmp_lt_i32_e32 vcc, v1, v208
	v_readlane_b32 s7, v251, 26
	s_add_u32 s2, s6, 0x1000
	v_cndmask_b32_e32 v1, v207, v1, vcc
	v_lshlrev_b32_e32 v25, 2, v1
	v_xor_b32_e32 v1, 4, v207
	v_cmp_lt_i32_e32 vcc, v1, v208
	v_readlane_b32 s4, v251, 23
	s_addc_u32 s3, s7, 0
	v_cndmask_b32_e32 v1, v207, v1, vcc
	v_lshlrev_b32_e32 v26, 2, v1
	v_xor_b32_e32 v1, 2, v207
	v_cmp_lt_i32_e32 vcc, v1, v208
	v_readlane_b32 s5, v251, 24
	s_add_u32 s4, s4, 0x1000
	v_cndmask_b32_e32 v1, v207, v1, vcc
	v_lshlrev_b32_e32 v27, 2, v1
	v_xor_b32_e32 v1, 1, v207
	v_cmp_lt_i32_e32 vcc, v1, v208
	s_addc_u32 s5, s5, 0
	v_mov_b32_e32 v3, 0
	v_cndmask_b32_e32 v1, v207, v1, vcc
	v_lshlrev_b32_e32 v28, 2, v1
	v_lshlrev_b32_e32 v1, 4, v206
	v_and_b32_e32 v2, 0x3f0, v1
	v_ashrrev_i32_e32 v1, 31, v0
	s_ashr_i32 s95, s94, 31
	v_lshl_add_u64 v[4:5], s[4:5], 0, v[2:3]
	v_lshl_add_u64 v[6:7], s[2:3], 0, v[2:3]
	v_or_b32_e32 v10, 0x400, v2
	v_or_b32_e32 v14, 0x800, v2
	v_or_b32_e32 v2, 0xc00, v2
	v_lshl_add_u64 v[0:1], v[0:1], 0, s[94:95]
	v_lshl_add_u64 v[16:17], s[4:5], 0, v[2:3]
	v_lshl_add_u64 v[18:19], s[2:3], 0, v[2:3]
	v_lshlrev_b64 v[0:1], 12, v[0:1]
	v_and_b32_e32 v2, 63, v206
	v_readlane_b32 s1, v251, 20
	v_readlane_b32 s8, v251, 27
	v_readlane_b32 s9, v251, 28
	s_lshl_b32 s0, s72, 3
	v_mov_b32_e32 v11, v3
	v_mov_b32_e32 v15, v3
	v_lshl_or_b32 v0, v2, 4, v0
	v_lshl_add_u64 v[8:9], s[4:5], 0, v[10:11]
	v_lshl_add_u64 v[10:11], s[2:3], 0, v[10:11]
	v_lshl_add_u64 v[12:13], s[4:5], 0, v[14:15]
	v_lshl_add_u64 v[14:15], s[2:3], 0, v[14:15]
	v_lshl_add_u64 v[0:1], s[8:9], 0, v[0:1]
	s_mov_b64 s[2:3], 0x800
	s_ashr_i32 s1, s0, 31
	v_lshl_add_u64 v[20:21], v[0:1], 0, s[2:3]
	s_lshl_b64 s[2:3], s[0:1], 12
	s_mov_b64 s[4:5], 0
	v_mov_b32_e32 v29, 0x3727c5ac
	s_mov_b32 s1, 0x800000
	s_movk_i32 s6, 0x7fff
	v_readlane_b32 s10, v251, 29
	v_readlane_b32 s11, v251, 30
	v_readlane_b32 s12, v251, 31
	v_readlane_b32 s13, v251, 32
	v_readlane_b32 s14, v251, 33
	v_readlane_b32 s15, v251, 34
	global_load_dwordx4 v[64:67], v[4:5], off
	global_load_dwordx4 v[80:83], v[6:7], off
	global_load_dwordx4 v[68:71], v[8:9], off
	global_load_dwordx4 v[84:87], v[10:11], off
	global_load_dwordx4 v[72:75], v[12:13], off
	global_load_dwordx4 v[88:91], v[14:15], off
	global_load_dwordx4 v[76:79], v[16:17], off
	global_load_dwordx4 v[92:95], v[18:19], off
	global_load_dwordx4 v[96:99], v[20:21], off offset:-2048
	global_load_dwordx4 v[100:103], v[20:21], off offset:-1024
	global_load_dwordx4 v[104:107], v[20:21], off
	global_load_dwordx4 v[108:111], v[20:21], off offset:1024
	s_waitcnt vmcnt(0)
; DI void st4(bf16_t* p, float a, float b, float c, float d) { u32x2 w = {pk2(a, b), pk2(c, d)}; *(u32x2*)p = w; }
; DI void phase_ln(const Params& p, const float* g, const float* bta, const float* sh, const float* sc, bool writex, int bid, int nb) {
;     ...
;     float* xr = p.out + (size_t)row * DM; const int b = row >> 12;
;     f32x4 v[4]; float s = 0.f;
; #pragma unroll
;     for (int e = 0; e < 4; ++e) { v[e] = *(const f32x4*)(xr + e * 256 + lane * 4); s += (v[e][0] + v[e][1]) + (v[e][2] + v[e][3]); }
; #pragma unroll
;     for (int o = 32; o > 0; o >>= 1) s += __shfl_xor(s, o);
;     const float mu = s * (1.f / 1024.f); float q = 0.f;
; #pragma unroll
;     for (int e = 0; e < 4; ++e) { v[e] -= mu; q += (v[e][0] * v[e][0] + v[e][1] * v[e][1]) + (v[e][2] * v[e][2] + v[e][3] * v[e][3]); }
; #pragma unroll
;     for (int o = 32; o > 0; o >>= 1) q += __shfl_xor(q, o);
;     const float rstd = rsqrtf(q * (1.f / 1024.f) + 1e-5f);
;     if (!writex && lane == 0) { f32x2 ms = {mu, rstd}; *(f32x2*)(p.lnstat + (size_t)row * 2) = ms; }
; #pragma unroll
;     for (int e = 0; e < 4; ++e) { const int col = e * 256 + lane * 4;
;       const f32x4 y = v[e] * rstd * *(const f32x4*)(g + col) + *(const f32x4*)(bta + col);
;       if (writex) *(f32x4*)(xr + col) = y;
;       if (sh) { const f32x4 hv = y * (*(const f32x4*)(sc + b * 6144 + col) + 1.f) + *(const f32x4*)(sh + b * 6144 + col); st4(p.H + (size_t)row * DM + col, hv[0], hv[1], hv[2], hv[3]); } }
.LBB0_2111:
	s_waitcnt vmcnt(4)
	v_mov_b64_e32 v[30:31], v[96:97]
	v_mov_b64_e32 v[32:33], v[98:99]
	v_mov_b64_e32 v[34:35], v[100:101]
	v_mov_b64_e32 v[36:37], v[102:103]
	v_mov_b64_e32 v[38:39], v[104:105]
	v_mov_b64_e32 v[40:41], v[106:107]
	v_mov_b64_e32 v[0:1], v[108:109]
	v_mov_b64_e32 v[2:3], v[110:111]
	v_add_u32_e32 v112, s0, v22
	v_cmp_ge_i32_e64 s[98:99], s6, v112
	v_lshl_add_u64 v[114:115], v[20:21], 0, s[2:3]
	s_nop 1
	v_cndmask_b32_e64 v114, v20, v114, s[98:99]
	v_cndmask_b32_e64 v115, v21, v115, s[98:99]
	global_load_dwordx4 v[96:99], v[114:115], off offset:-2048
	global_load_dwordx4 v[100:103], v[114:115], off offset:-1024
	global_load_dwordx4 v[104:107], v[114:115], off
	global_load_dwordx4 v[108:111], v[114:115], off offset:1024
	v_add_u32_e32 v22, s0, v22
	v_mov_b32_e32 v42, v31
	v_mov_b32_e32 v43, v32
	v_mov_b32_e32 v44, v30
	v_mov_b32_e32 v45, v33
	v_mov_b32_e32 v46, v35
	v_mov_b32_e32 v47, v36
	v_mov_b32_e32 v48, v34
	v_mov_b32_e32 v49, v37
	v_pk_add_f32 v[42:43], v[42:43], v[44:45]
	v_pk_add_f32 v[44:45], v[46:47], v[48:49]
	v_add_f32_e32 v48, v42, v43
	v_pk_add_f32 v[42:43], v[44:45], v[44:45] op_sel:[0,1] op_sel_hi:[1,0]
	v_add_f32_e32 v50, v38, v39
	v_add_f32_e32 v52, v40, v41
	v_mov_b32_e32 v55, v0
	v_mov_b32_e32 v51, v2
	v_mov_b32_e32 v53, v3
	v_add_f32_e32 v54, 0, v48
	v_mov_b32_e32 v43, v1
	v_pk_add_f32 v[46:47], v[50:51], v[52:53]
	v_pk_add_f32 v[42:43], v[54:55], v[42:43]
	s_nop 0
	v_pk_add_f32 v[42:43], v[42:43], v[46:47]
	s_nop 0
	v_add_f32_e32 v42, v42, v43
	ds_bpermute_b32 v43, v23, v42
	s_waitcnt lgkmcnt(0)
	v_add_f32_e32 v42, v42, v43
	ds_bpermute_b32 v43, v24, v42
	s_waitcnt lgkmcnt(0)
	v_add_f32_e32 v42, v42, v43
	ds_bpermute_b32 v43, v25, v42
	s_waitcnt lgkmcnt(0)
	v_add_f32_e32 v42, v42, v43
	ds_bpermute_b32 v43, v26, v42
	s_waitcnt lgkmcnt(0)
	v_add_f32_e32 v42, v42, v43
	ds_bpermute_b32 v43, v27, v42
	s_waitcnt lgkmcnt(0)
	v_add_f32_e32 v50, v42, v43
	ds_bpermute_b32 v51, v28, v50
	s_waitcnt lgkmcnt(0)
	v_add_f32_e32 v50, v50, v51
	v_fmamk_f32 v31, v50, 0xba800000, v31
	v_fmamk_f32 v30, v50, 0xba800000, v30
	v_fmamk_f32 v33, v50, 0xba800000, v33
	v_fmac_f32_e32 v32, 0xba800000, v50
	v_fmamk_f32 v35, v50, 0xba800000, v35
	v_fmamk_f32 v34, v50, 0xba800000, v34
	v_fmamk_f32 v37, v50, 0xba800000, v37
	v_fmac_f32_e32 v36, 0xba800000, v50
	v_fmamk_f32 v39, v50, 0xba800000, v39
	v_fmamk_f32 v38, v50, 0xba800000, v38
	v_fmamk_f32 v41, v50, 0xba800000, v41
	v_fmac_f32_e32 v40, 0xba800000, v50
	v_fmamk_f32 v3, v50, 0xba800000, v3
	v_fmamk_f32 v2, v50, 0xba800000, v2
	v_fmamk_f32 v1, v50, 0xba800000, v1
	v_fmac_f32_e32 v0, 0xba800000, v50
	v_pk_mul_f32 v[50:51], v[32:33], v[32:33]
	v_pk_mul_f32 v[52:53], v[30:31], v[30:31]
	v_pk_mul_f32 v[54:55], v[36:37], v[36:37]
	v_pk_mul_f32 v[56:57], v[34:35], v[34:35]
	v_pk_mov_b32 v[62:63], v[52:53], v[50:51] op_sel:[1,0]
	v_mov_b32_e32 v53, v51
	v_pk_mov_b32 v[50:51], v[56:57], v[54:55] op_sel:[1,0]
	v_mov_b32_e32 v57, v55
	v_mul_f32_e32 v58, v38, v38
	v_mul_f32_e32 v60, v40, v40
	v_pk_add_f32 v[52:53], v[62:63], v[52:53]
	v_pk_add_f32 v[50:51], v[50:51], v[56:57]
	v_pk_fma_f32 v[54:55], v[38:39], v[38:39], v[58:59] op_sel_hi:[1,1,0]
	v_pk_fma_f32 v[58:59], v[40:41], v[40:41], v[60:61] op_sel_hi:[1,1,0]
	v_pk_add_f32 v[52:53], v[52:53], v[52:53] op_sel_hi:[0,1]
	v_pk_add_f32 v[50:51], v[50:51], v[50:51] op_sel_hi:[0,1]
	v_mul_f32_e32 v54, v0, v0
	v_mul_f32_e32 v58, v1, v1
	v_mul_f32_e32 v52, v2, v2
	v_mul_f32_e32 v50, v3, v3
	v_pk_add_f32 v[54:55], v[54:55], v[58:59]
	v_pk_add_f32 v[50:51], v[52:53], v[50:51]
	s_nop 0
	v_pk_add_f32 v[50:51], v[54:55], v[50:51]
	s_nop 0
	v_add_f32_e32 v50, v50, v51
	ds_bpermute_b32 v51, v23, v50
	s_waitcnt lgkmcnt(0)
	v_add_f32_e32 v50, v50, v51
	ds_bpermute_b32 v51, v24, v50
	s_waitcnt lgkmcnt(0)
	v_add_f32_e32 v50, v50, v51
	ds_bpermute_b32 v51, v25, v50
	s_waitcnt lgkmcnt(0)
	v_add_f32_e32 v50, v50, v51
	ds_bpermute_b32 v51, v26, v50
	s_waitcnt lgkmcnt(0)
	v_add_f32_e32 v50, v50, v51
	ds_bpermute_b32 v51, v27, v50
	s_waitcnt lgkmcnt(0)
	v_add_f32_e32 v50, v50, v51
	ds_bpermute_b32 v51, v28, v50
	s_waitcnt lgkmcnt(0)
	v_add_f32_e32 v50, v50, v51
	v_fmamk_f32 v50, v50, 0x3a800000, v29
	v_mul_f32_e32 v51, 0x4b800000, v50
	v_cmp_gt_f32_e32 vcc, s1, v50
	s_nop 1
	v_cndmask_b32_e32 v50, v50, v51, vcc
	v_rsq_f32_e32 v50, v50
	s_nop 0
	v_mul_f32_e32 v51, 0x45800000, v50
	v_cndmask_b32_e32 v50, v50, v51, vcc
	v_pk_mul_f32 v[30:31], v[30:31], v[50:51] op_sel_hi:[1,0]
	v_pk_mul_f32 v[32:33], v[32:33], v[50:51] op_sel_hi:[1,0]
	v_pk_mul_f32 v[34:35], v[34:35], v[50:51] op_sel_hi:[1,0]
	v_pk_mul_f32 v[36:37], v[36:37], v[50:51] op_sel_hi:[1,0]
	v_pk_mul_f32 v[38:39], v[38:39], v[50:51] op_sel_hi:[1,0]
	v_pk_mul_f32 v[40:41], v[40:41], v[50:51] op_sel_hi:[1,0]
	v_pk_mul_f32 v[0:1], v[0:1], v[50:51] op_sel_hi:[1,0]
	v_pk_mul_f32 v[2:3], v[2:3], v[50:51] op_sel_hi:[1,0]
	v_cmp_lt_i32_e32 vcc, s6, v22
	s_or_b64 s[4:5], vcc, s[4:5]
	v_pk_fma_f32 v[30:31], v[64:65], v[30:31], v[80:81]
	v_pk_fma_f32 v[32:33], v[66:67], v[32:33], v[82:83]
	v_pk_fma_f32 v[34:35], v[68:69], v[34:35], v[84:85]
	v_pk_fma_f32 v[36:37], v[70:71], v[36:37], v[86:87]
	v_pk_fma_f32 v[38:39], v[72:73], v[38:39], v[88:89]
	v_pk_fma_f32 v[40:41], v[74:75], v[40:41], v[90:91]
	v_pk_fma_f32 v[0:1], v[76:77], v[0:1], v[92:93]
	v_pk_fma_f32 v[2:3], v[78:79], v[2:3], v[94:95]
	global_store_dwordx4 v[20:21], v[30:33], off offset:-2048
	global_store_dwordx4 v[20:21], v[34:37], off offset:-1024
	global_store_dwordx4 v[20:21], v[38:41], off
	global_store_dwordx4 v[20:21], v[0:3], off offset:1024
	v_lshl_add_u64 v[20:21], v[20:21], 0, s[2:3]
	s_andn2_b64 exec, exec, s[4:5]
	s_cbranch_execnz .LBB0_2111
